# score tail: second scale gather addressed through an SGPR base (3 VALU + 1 nop fewer per expert)
# speedup vs baseline: 1.0058x; 1.0006x over previous
; DEV void phase_peer_score(const Params& p, int layer, int M, char* smem) {
;     ...
;     float ev[16]; float sum = 0.f;
; #pragma unroll
;     for (int t = 0; t < 16; t++) { ev[t] = __expf(R[t] - R[0]); sum += ev[t]; }
;     const float inv = 1.f / sum;
;     int eid[16];
; #pragma unroll
;     for (int t = 0; t < 16; t++) {
;       unsigned code = __float_as_uint(R[t]) & 255u;
;       eid[t] = (int)tab[code >> 4] * 128 + (int)tab[16 + (code & 15u)];
;     }
.Lmed3_ok_bb_172:
	s_lshl_b32 s0, s18, 3
	s_andn2_b32 s0, s0, 63
	v_add_u32_e32 v18, s0, v117
	s_movk_i32 s0, 0xff00
	v_sub_f32_e32 v5, v164, v148
	v_mul_f32_e32 v5, 0x3fb8aa3b, v5
	v_exp_f32_e32 v101, v5
	v_sub_f32_e32 v5, v149, v148
	v_mul_f32_e32 v5, 0x3fb8aa3b, v5
	v_exp_f32_e32 v104, v5
	v_sub_f32_e32 v5, v150, v148
	v_mul_f32_e32 v5, 0x3fb8aa3b, v5
	v_exp_f32_e32 v105, v5
	v_sub_f32_e32 v5, v151, v148
	v_mul_f32_e32 v5, 0x3fb8aa3b, v5
	v_exp_f32_e32 v102, v5
	v_sub_f32_e32 v5, v152, v148
	v_mul_f32_e32 v5, 0x3fb8aa3b, v5
	v_exp_f32_e32 v103, v5
	v_sub_f32_e32 v5, v153, v148
	v_mul_f32_e32 v5, 0x3fb8aa3b, v5
	v_exp_f32_e32 v110, v5
	v_sub_f32_e32 v5, v154, v148
	v_sub_f32_e32 v3, v148, v148
	v_mul_f32_e32 v5, 0x3fb8aa3b, v5
	v_mul_f32_e32 v3, 0x3fb8aa3b, v3
	v_exp_f32_e32 v111, v5
	v_sub_f32_e32 v5, v155, v148
	v_exp_f32_e32 v100, v3
	v_mul_f32_e32 v5, 0x3fb8aa3b, v5
	v_exp_f32_e32 v112, v5
	v_sub_f32_e32 v5, v156, v148
	v_mul_f32_e32 v5, 0x3fb8aa3b, v5
	v_exp_f32_e32 v113, v5
	v_sub_f32_e32 v5, v157, v148
	v_add_f32_e32 v3, 0, v100
	v_mul_f32_e32 v5, 0x3fb8aa3b, v5
	v_add_f32_e32 v3, v3, v101
	v_exp_f32_e32 v114, v5
	v_sub_f32_e32 v5, v158, v148
	v_add_f32_e32 v3, v3, v104
	v_mul_f32_e32 v5, 0x3fb8aa3b, v5
	v_add_f32_e32 v3, v3, v105
	v_exp_f32_e32 v115, v5
	v_sub_f32_e32 v5, v159, v148
	v_add_f32_e32 v3, v3, v102
	v_mul_f32_e32 v5, 0x3fb8aa3b, v5
	v_add_f32_e32 v3, v3, v103
	v_exp_f32_e32 v106, v5
	v_sub_f32_e32 v5, v160, v148
	v_add_f32_e32 v3, v3, v110
	v_mul_f32_e32 v5, 0x3fb8aa3b, v5
	v_add_f32_e32 v3, v3, v111
	v_exp_f32_e32 v107, v5
	v_sub_f32_e32 v5, v161, v148
	v_add_f32_e32 v3, v3, v112
	v_mul_f32_e32 v5, 0x3fb8aa3b, v5
	v_add_f32_e32 v3, v3, v113
	v_exp_f32_e32 v108, v5
	v_sub_f32_e32 v5, v162, v148
	v_add_f32_e32 v3, v3, v114
	v_mul_f32_e32 v5, 0x3fb8aa3b, v5
	v_add_f32_e32 v3, v3, v115
	v_exp_f32_e32 v109, v5
	v_add_f32_e32 v3, v3, v106
	v_add_f32_e32 v3, v3, v107
	v_add_f32_e32 v3, v3, v108
	v_add_f32_e32 v3, v3, v109
	v_div_scale_f32 v5, s[0:1], v3, v3, 1.0
	v_rcp_f32_e32 v6, v5
	v_ashrrev_i32_e32 v19, 31, v18
	s_mov_b32 s0, 0x10000
	v_lshlrev_b64 v[120:121], 9, v[18:19]
	v_fma_f32 v17, -v5, v6, 1.0
	v_fmac_f32_e32 v6, v17, v6
	v_div_scale_f32 v17, vcc, 1.0, v3, 1.0
	v_mul_f32_e32 v20, v17, v6
	v_fma_f32 v21, -v5, v20, v17
	v_fmac_f32_e32 v20, v21, v6
	v_fma_f32 v5, -v5, v20, v17
	v_div_fmas_f32 v5, v5, v6, v20
	v_div_fixup_f32 v116, v5, v3, 1.0
	v_bfe_u32 v3, v162, 4, 4
	v_and_b32_e32 v2, 15, v162
	v_and_b32_e32 v17, 15, v154
	v_add_u32_e32 v3, v138, v3
	v_add_u32_e32 v2, v138, v2
	v_add_u32_e32 v17, v138, v17
	ds_read_u8 v3, v3
	ds_read_u8 v17, v17 offset:16
	ds_read_u8 v2, v2 offset:16
	v_and_b32_e32 v6, 15, v159
	v_add_u32_e32 v6, v138, v6
	ds_read_u8 v6, v6 offset:16
	v_lshl_add_u64 v[18:19], s[8:9], 0, v[120:121]
	s_waitcnt lgkmcnt(1)
	v_lshl_add_u32 v5, v3, 7, v2
	v_bfe_u32 v2, v161, 4, 4
	v_and_b32_e32 v3, 15, v161
	v_add_u32_e32 v2, v138, v2
	v_add_u32_e32 v3, v138, v3
	ds_read_u8 v2, v2
	ds_read_u8 v3, v3 offset:16
	s_lshl_b32 s52, s19, 6
	v_lshl_add_u64 v[118:119], v[18:19], 0, s[52:53]
	v_lshl_add_u64 v[120:121], s[6:7], 0, v[120:121]
	v_lshl_add_u64 v[120:121], v[120:121], 0, s[52:53]
	s_waitcnt lgkmcnt(0)
	v_lshl_add_u32 v4, v2, 7, v3
	v_bfe_u32 v2, v160, 4, 4
	v_and_b32_e32 v3, 15, v160
	v_add_u32_e32 v2, v138, v2
	v_add_u32_e32 v3, v138, v3
	ds_read_u8 v2, v2
	ds_read_u8 v3, v3 offset:16
	v_and_b32_e32 v7, 15, v158
	v_add_u32_e32 v7, v138, v7
	ds_read_u8 v7, v7 offset:16
	s_waitcnt lgkmcnt(1)
	v_lshl_add_u32 v3, v2, 7, v3
	v_bfe_u32 v2, v159, 4, 4
	v_add_u32_e32 v2, v138, v2
	ds_read_u8 v2, v2
	s_waitcnt lgkmcnt(0)
	v_lshl_add_u32 v2, v2, 7, v6
	v_bfe_u32 v6, v158, 4, 4
	v_add_u32_e32 v6, v138, v6
	ds_read_u8 v6, v6
	s_waitcnt lgkmcnt(0)
	v_lshl_add_u32 v9, v6, 7, v7
	v_bfe_u32 v6, v157, 4, 4
	v_and_b32_e32 v7, 15, v157
	v_add_u32_e32 v6, v138, v6
	v_add_u32_e32 v7, v138, v7
	ds_read_u8 v6, v6
	ds_read_u8 v7, v7 offset:16
	s_waitcnt lgkmcnt(0)
	v_lshl_add_u32 v8, v6, 7, v7
	v_bfe_u32 v6, v156, 4, 4
	v_and_b32_e32 v7, 15, v156
	v_add_u32_e32 v6, v138, v6
	v_add_u32_e32 v7, v138, v7
	ds_read_u8 v6, v6
	ds_read_u8 v7, v7 offset:16
	s_waitcnt lgkmcnt(0)
	v_lshl_add_u32 v7, v6, 7, v7
	v_bfe_u32 v6, v155, 4, 4
	v_and_b32_e32 v13, 15, v155
	v_add_u32_e32 v6, v138, v6
	v_add_u32_e32 v13, v138, v13
	ds_read_u8 v6, v6
	ds_read_u8 v13, v13 offset:16
	s_waitcnt lgkmcnt(0)
	v_lshl_add_u32 v6, v6, 7, v13
	v_bfe_u32 v13, v154, 4, 4
	v_add_u32_e32 v13, v138, v13
	ds_read_u8 v13, v13
	s_waitcnt lgkmcnt(0)
	v_lshl_add_u32 v13, v13, 7, v17
	v_bfe_u32 v17, v153, 4, 4
	v_and_b32_e32 v12, 15, v153
	v_add_u32_e32 v17, v138, v17
	v_add_u32_e32 v12, v138, v12
	ds_read_u8 v17, v17
	ds_read_u8 v12, v12 offset:16
	s_waitcnt lgkmcnt(0)
; DEV void phase_peer_score(const Params& p, int layer, int M, char* smem) {
;     ...
;     for (int t = 0; t < 16; t++) {
;       unsigned code = __float_as_uint(R[t]) & 255u;
;       eid[t] = (int)tab[code >> 4] * 128 + (int)tab[16 + (code & 15u)];
;     }
;     if (quad == 0) {
;       int* eo = EIDX + (size_t)m * 128 + h * 16;
;       float* go = GATE + (size_t)m * 128 + h * 16;
;       float* uo = go + (size_t)MT * 128;
;       float us[16], vs[16];
; #pragma unroll
;       for (int t = 0; t < 16; t++) { us[t] = USC[eid[t]]; vs[t] = USC[16384 + eid[t]]; }
; #pragma unroll
;       for (int t = 0; t < 16; t += 4) {
;         *(int4*)(eo + t) = make_int4(eid[t], eid[t + 1], eid[t + 2], eid[t + 3]);
;         *(float4*)(go + t) = make_float4(ev[t] * inv * vs[t], ev[t + 1] * inv * vs[t + 1], ev[t + 2] * inv * vs[t + 2], ev[t + 3] * inv * vs[t + 3]);
;         *(float4*)(uo + t) = make_float4(us[t], us[t + 1], us[t + 2], us[t + 3]);
;       }
	v_lshl_add_u32 v12, v17, 7, v12
	v_bfe_u32 v17, v152, 4, 4
	v_and_b32_e32 v11, 15, v152
	v_add_u32_e32 v17, v138, v17
	v_add_u32_e32 v11, v138, v11
	ds_read_u8 v17, v17
	ds_read_u8 v11, v11 offset:16
	s_waitcnt lgkmcnt(0)
	v_lshl_add_u32 v11, v17, 7, v11
	v_bfe_u32 v17, v151, 4, 4
	v_and_b32_e32 v10, 15, v151
	v_add_u32_e32 v17, v138, v17
	v_add_u32_e32 v10, v138, v10
	ds_read_u8 v17, v17
	ds_read_u8 v10, v10 offset:16
	s_waitcnt lgkmcnt(0)
	v_lshl_add_u32 v10, v17, 7, v10
	v_bfe_u32 v17, v150, 4, 4
	v_and_b32_e32 v16, 15, v150
	v_add_u32_e32 v17, v138, v17
	v_add_u32_e32 v16, v138, v16
	ds_read_u8 v17, v17
	ds_read_u8 v16, v16 offset:16
	s_waitcnt lgkmcnt(0)
	v_lshl_add_u32 v17, v17, 7, v16
	v_bfe_u32 v16, v149, 4, 4
	v_and_b32_e32 v15, 15, v149
	v_add_u32_e32 v16, v138, v16
	v_add_u32_e32 v15, v138, v15
	ds_read_u8 v16, v16
	ds_read_u8 v15, v15 offset:16
	s_waitcnt lgkmcnt(0)
	v_lshl_add_u32 v16, v16, 7, v15
	v_bfe_u32 v15, v164, 4, 4
	v_and_b32_e32 v14, 15, v164
	v_add_u32_e32 v15, v138, v15
	v_add_u32_e32 v14, v138, v14
	ds_read_u8 v15, v15
	ds_read_u8 v14, v14 offset:16
	s_waitcnt lgkmcnt(0)
	v_lshl_add_u32 v15, v15, 7, v14
	v_bfe_u32 v14, v148, 4, 4
	v_and_b32_e32 v0, 15, v148
	v_add_u32_e32 v14, v138, v14
	v_add_u32_e32 v0, v138, v0
	ds_read_u8 v14, v14
	ds_read_u8 v0, v0 offset:16
	s_waitcnt lgkmcnt(0)
	v_lshl_add_u32 v14, v14, 7, v0
	s_add_u32 s42, s10, 0x10000
	s_addc_u32 s43, s11, 0
	v_lshlrev_b32_e32 v0, 2, v14
	global_load_dword v18, v0, s[10:11]
	global_load_dword v122, v0, s[42:43]
	v_lshlrev_b32_e32 v0, 2, v15
	global_load_dword v19, v0, s[10:11]
	global_load_dword v123, v0, s[42:43]
	v_lshlrev_b32_e32 v0, 2, v16
	global_load_dword v20, v0, s[10:11]
	global_load_dword v126, v0, s[42:43]
	v_lshlrev_b32_e32 v0, 2, v17
	global_load_dword v21, v0, s[10:11]
	global_load_dword v127, v0, s[42:43]
	v_lshlrev_b32_e32 v0, 2, v10
	global_load_dword v22, v0, s[10:11]
	global_load_dword v124, v0, s[42:43]
	v_lshlrev_b32_e32 v0, 2, v11
	global_load_dword v23, v0, s[10:11]
	global_load_dword v125, v0, s[42:43]
	v_lshlrev_b32_e32 v0, 2, v12
	global_load_dword v24, v0, s[10:11]
	global_load_dword v128, v0, s[42:43]
	v_lshlrev_b32_e32 v0, 2, v13
	global_load_dword v25, v0, s[10:11]
	global_load_dword v129, v0, s[42:43]
	v_lshlrev_b32_e32 v0, 2, v6
	global_load_dword v26, v0, s[10:11]
	global_load_dword v130, v0, s[42:43]
	v_lshlrev_b32_e32 v0, 2, v7
	global_load_dword v27, v0, s[10:11]
	global_load_dword v131, v0, s[42:43]
	v_lshlrev_b32_e32 v0, 2, v8
	global_load_dword v28, v0, s[10:11]
	global_load_dword v132, v0, s[42:43]
	v_lshlrev_b32_e32 v0, 2, v9
	global_load_dword v29, v0, s[10:11]
	global_load_dword v133, v0, s[42:43]
	v_lshlrev_b32_e32 v0, 2, v2
	global_load_dword v30, v0, s[10:11]
	global_load_dword v134, v0, s[42:43]
	v_lshlrev_b32_e32 v0, 2, v3
	global_load_dword v31, v0, s[10:11]
	global_load_dword v135, v0, s[42:43]
	v_lshlrev_b32_e32 v0, 2, v4
	global_load_dword v32, v0, s[10:11]
	global_load_dword v136, v0, s[42:43]
	v_lshlrev_b32_e32 v0, 2, v5
	global_load_dword v33, v0, s[10:11]
	global_load_dword v137, v0, s[42:43]
	s_mov_b32 s0, 0x840000
	global_store_dwordx4 v[120:121], v[14:17], off
	s_nop 1
	v_pk_mul_f32 v[14:15], v[100:101], v[116:117] op_sel_hi:[1,0]
	v_pk_mul_f32 v[16:17], v[104:105], v[116:117] op_sel_hi:[1,0]
	s_waitcnt vmcnt(29)
	v_pk_mul_f32 v[14:15], v[14:15], v[122:123]
	s_waitcnt vmcnt(25)
	v_pk_mul_f32 v[16:17], v[16:17], v[126:127]
	global_store_dwordx4 v[118:119], v[14:17], off
	s_nop 1
	v_add_co_u32_e32 v14, vcc, s0, v118
	s_nop 1
	v_addc_co_u32_e32 v15, vcc, 0, v119, vcc
	global_store_dwordx4 v[14:15], v[18:21], off
	global_store_dwordx4 v[120:121], v[10:13], off offset:16
	s_nop 1
	v_pk_mul_f32 v[10:11], v[102:103], v[116:117] op_sel_hi:[1,0]
	v_pk_mul_f32 v[12:13], v[110:111], v[116:117] op_sel_hi:[1,0]
	s_waitcnt vmcnt(24)
	v_pk_mul_f32 v[10:11], v[10:11], v[124:125]
	s_waitcnt vmcnt(20)
	v_pk_mul_f32 v[12:13], v[12:13], v[128:129]
	global_store_dwordx4 v[118:119], v[10:13], off offset:16
	global_store_dwordx4 v[14:15], v[22:25], off offset:16
	global_store_dwordx4 v[120:121], v[6:9], off offset:32
	s_nop 1
	v_pk_mul_f32 v[6:7], v[112:113], v[116:117] op_sel_hi:[1,0]
	v_pk_mul_f32 v[8:9], v[114:115], v[116:117] op_sel_hi:[1,0]
	s_waitcnt vmcnt(19)
	v_pk_mul_f32 v[6:7], v[6:7], v[130:131]
	s_waitcnt vmcnt(15)
	v_pk_mul_f32 v[8:9], v[8:9], v[132:133]
	global_store_dwordx4 v[118:119], v[6:9], off offset:32
	global_store_dwordx4 v[14:15], v[26:29], off offset:32
	global_store_dwordx4 v[120:121], v[2:5], off offset:48
	s_nop 1
	v_pk_mul_f32 v[2:3], v[106:107], v[116:117] op_sel_hi:[1,0]
	v_pk_mul_f32 v[4:5], v[108:109], v[116:117] op_sel_hi:[1,0]
	s_waitcnt vmcnt(14)
	v_pk_mul_f32 v[2:3], v[2:3], v[134:135]
	s_waitcnt vmcnt(10)
	v_pk_mul_f32 v[4:5], v[4:5], v[136:137]
	global_store_dwordx4 v[118:119], v[2:5], off offset:48
	global_store_dwordx4 v[14:15], v[30:33], off offset:48
	s_branch .LBB0_162

; DEV void phase_peer_score(const Params& p, int layer, int M, char* smem) {
;     ...
;     float ev[16]; float sum = 0.f;
; #pragma unroll
;     for (int t = 0; t < 16; t++) { ev[t] = __expf(R[t] - R[0]); sum += ev[t]; }
;     const float inv = 1.f / sum;
;     int eid[16];
; #pragma unroll
;     for (int t = 0; t < 16; t++) {
;       unsigned code = __float_as_uint(R[t]) & 255u;
;       eid[t] = (int)tab[code >> 4] * 128 + (int)tab[16 + (code & 15u)];
;     }
.Lmed3_ok_bb_637:
	s_lshl_b32 s18, s16, 3
	s_andn2_b32 s18, s18, 63
	v_add_u32_e32 v18, s18, v117
	s_movk_i32 s18, 0xff00
	v_sub_f32_e32 v5, v164, v148
	v_mul_f32_e32 v5, 0x3fb8aa3b, v5
	v_exp_f32_e32 v101, v5
	v_sub_f32_e32 v5, v149, v148
	v_mul_f32_e32 v5, 0x3fb8aa3b, v5
	v_exp_f32_e32 v104, v5
	v_sub_f32_e32 v5, v150, v148
	v_mul_f32_e32 v5, 0x3fb8aa3b, v5
	v_exp_f32_e32 v105, v5
	v_sub_f32_e32 v5, v151, v148
	v_mul_f32_e32 v5, 0x3fb8aa3b, v5
	v_exp_f32_e32 v102, v5
	v_sub_f32_e32 v5, v152, v148
	v_mul_f32_e32 v5, 0x3fb8aa3b, v5
	v_exp_f32_e32 v103, v5
	v_sub_f32_e32 v5, v153, v148
	v_mul_f32_e32 v5, 0x3fb8aa3b, v5
	v_exp_f32_e32 v110, v5
	v_sub_f32_e32 v5, v154, v148
	v_sub_f32_e32 v3, v148, v148
	v_mul_f32_e32 v5, 0x3fb8aa3b, v5
	v_mul_f32_e32 v3, 0x3fb8aa3b, v3
	v_exp_f32_e32 v111, v5
	v_sub_f32_e32 v5, v155, v148
	v_exp_f32_e32 v100, v3
	v_mul_f32_e32 v5, 0x3fb8aa3b, v5
	v_exp_f32_e32 v112, v5
	v_sub_f32_e32 v5, v156, v148
	v_mul_f32_e32 v5, 0x3fb8aa3b, v5
	v_exp_f32_e32 v113, v5
	v_sub_f32_e32 v5, v157, v148
	v_add_f32_e32 v3, 0, v100
	v_mul_f32_e32 v5, 0x3fb8aa3b, v5
	v_add_f32_e32 v3, v3, v101
	v_exp_f32_e32 v114, v5
	v_sub_f32_e32 v5, v158, v148
	v_add_f32_e32 v3, v3, v104
	v_mul_f32_e32 v5, 0x3fb8aa3b, v5
	v_add_f32_e32 v3, v3, v105
	v_exp_f32_e32 v115, v5
	v_sub_f32_e32 v5, v159, v148
	v_add_f32_e32 v3, v3, v102
	v_mul_f32_e32 v5, 0x3fb8aa3b, v5
	v_add_f32_e32 v3, v3, v103
	v_exp_f32_e32 v106, v5
	v_sub_f32_e32 v5, v160, v148
	v_add_f32_e32 v3, v3, v110
	v_mul_f32_e32 v5, 0x3fb8aa3b, v5
	v_add_f32_e32 v3, v3, v111
	v_exp_f32_e32 v107, v5
	v_sub_f32_e32 v5, v161, v148
	v_add_f32_e32 v3, v3, v112
	v_mul_f32_e32 v5, 0x3fb8aa3b, v5
	v_add_f32_e32 v3, v3, v113
	v_exp_f32_e32 v108, v5
	v_sub_f32_e32 v5, v162, v148
	v_add_f32_e32 v3, v3, v114
	v_mul_f32_e32 v5, 0x3fb8aa3b, v5
	v_add_f32_e32 v3, v3, v115
	v_exp_f32_e32 v109, v5
	v_add_f32_e32 v3, v3, v106
	v_add_f32_e32 v3, v3, v107
	v_add_f32_e32 v3, v3, v108
	v_add_f32_e32 v3, v3, v109
	v_div_scale_f32 v5, s[18:19], v3, v3, 1.0
	v_rcp_f32_e32 v6, v5
	v_ashrrev_i32_e32 v19, 31, v18
	s_lshl_b32 s52, s17, 6
	s_mov_b32 s17, 0x10000
	v_fma_f32 v17, -v5, v6, 1.0
	v_fmac_f32_e32 v6, v17, v6
	v_div_scale_f32 v17, vcc, 1.0, v3, 1.0
	v_mul_f32_e32 v20, v17, v6
	v_fma_f32 v21, -v5, v20, v17
	v_fmac_f32_e32 v20, v21, v6
	v_fma_f32 v5, -v5, v20, v17
	v_div_fmas_f32 v5, v5, v6, v20
	v_div_fixup_f32 v116, v5, v3, 1.0
	v_bfe_u32 v3, v162, 4, 4
	v_and_b32_e32 v2, 15, v162
	v_and_b32_e32 v17, 15, v154
	v_add_u32_e32 v3, v138, v3
	v_add_u32_e32 v2, v138, v2
	v_add_u32_e32 v17, v138, v17
	ds_read_u8 v3, v3
	ds_read_u8 v17, v17 offset:16
	ds_read_u8 v2, v2 offset:16
	v_and_b32_e32 v6, 15, v159
	v_add_u32_e32 v6, v138, v6
	ds_read_u8 v6, v6 offset:16
	v_lshlrev_b64 v[120:121], 9, v[18:19]
	s_waitcnt lgkmcnt(1)
	v_lshl_add_u32 v5, v3, 7, v2
	v_bfe_u32 v2, v161, 4, 4
	v_and_b32_e32 v3, 15, v161
	v_add_u32_e32 v2, v138, v2
	v_add_u32_e32 v3, v138, v3
	ds_read_u8 v2, v2
	ds_read_u8 v3, v3 offset:16
	v_lshl_add_u64 v[18:19], s[2:3], 0, v[120:121]
	v_lshl_add_u64 v[118:119], v[18:19], 0, s[52:53]
	v_lshl_add_u64 v[120:121], s[0:1], 0, v[120:121]
	v_lshl_add_u64 v[120:121], v[120:121], 0, s[52:53]
	s_waitcnt lgkmcnt(0)
	v_lshl_add_u32 v4, v2, 7, v3
	v_bfe_u32 v2, v160, 4, 4
	v_and_b32_e32 v3, 15, v160
	v_add_u32_e32 v2, v138, v2
	v_add_u32_e32 v3, v138, v3
	ds_read_u8 v2, v2
	ds_read_u8 v3, v3 offset:16
	v_and_b32_e32 v7, 15, v158
	v_add_u32_e32 v7, v138, v7
	ds_read_u8 v7, v7 offset:16
	s_waitcnt lgkmcnt(1)
	v_lshl_add_u32 v3, v2, 7, v3
	v_bfe_u32 v2, v159, 4, 4
	v_add_u32_e32 v2, v138, v2
	ds_read_u8 v2, v2
	s_waitcnt lgkmcnt(0)
	v_lshl_add_u32 v2, v2, 7, v6
	v_bfe_u32 v6, v158, 4, 4
	v_add_u32_e32 v6, v138, v6
	ds_read_u8 v6, v6
	s_waitcnt lgkmcnt(0)
	v_lshl_add_u32 v9, v6, 7, v7
	v_bfe_u32 v6, v157, 4, 4
	v_and_b32_e32 v7, 15, v157
	v_add_u32_e32 v6, v138, v6
	v_add_u32_e32 v7, v138, v7
	ds_read_u8 v6, v6
	ds_read_u8 v7, v7 offset:16
	s_waitcnt lgkmcnt(0)
	v_lshl_add_u32 v8, v6, 7, v7
	v_bfe_u32 v6, v156, 4, 4
	v_and_b32_e32 v7, 15, v156
	v_add_u32_e32 v6, v138, v6
	v_add_u32_e32 v7, v138, v7
	ds_read_u8 v6, v6
	ds_read_u8 v7, v7 offset:16
	s_waitcnt lgkmcnt(0)
	v_lshl_add_u32 v7, v6, 7, v7
	v_bfe_u32 v6, v155, 4, 4
	v_and_b32_e32 v13, 15, v155
	v_add_u32_e32 v6, v138, v6
	v_add_u32_e32 v13, v138, v13
	ds_read_u8 v6, v6
	ds_read_u8 v13, v13 offset:16
	s_waitcnt lgkmcnt(0)
	v_lshl_add_u32 v6, v6, 7, v13
	v_bfe_u32 v13, v154, 4, 4
	v_add_u32_e32 v13, v138, v13
	ds_read_u8 v13, v13
	s_waitcnt lgkmcnt(0)
	v_lshl_add_u32 v13, v13, 7, v17
	v_bfe_u32 v17, v153, 4, 4
	v_and_b32_e32 v12, 15, v153
	v_add_u32_e32 v17, v138, v17
	v_add_u32_e32 v12, v138, v12
	ds_read_u8 v17, v17
	ds_read_u8 v12, v12 offset:16
	s_waitcnt lgkmcnt(0)
; DEV void phase_peer_score(const Params& p, int layer, int M, char* smem) {
;     ...
;     for (int t = 0; t < 16; t++) {
;       unsigned code = __float_as_uint(R[t]) & 255u;
;       eid[t] = (int)tab[code >> 4] * 128 + (int)tab[16 + (code & 15u)];
;     }
;     if (quad == 0) {
;       int* eo = EIDX + (size_t)m * 128 + h * 16;
;       float* go = GATE + (size_t)m * 128 + h * 16;
;       float* uo = go + (size_t)MT * 128;
;       float us[16], vs[16];
; #pragma unroll
;       for (int t = 0; t < 16; t++) { us[t] = USC[eid[t]]; vs[t] = USC[16384 + eid[t]]; }
; #pragma unroll
;       for (int t = 0; t < 16; t += 4) {
;         *(int4*)(eo + t) = make_int4(eid[t], eid[t + 1], eid[t + 2], eid[t + 3]);
;         *(float4*)(go + t) = make_float4(ev[t] * inv * vs[t], ev[t + 1] * inv * vs[t + 1], ev[t + 2] * inv * vs[t + 2], ev[t + 3] * inv * vs[t + 3]);
;         *(float4*)(uo + t) = make_float4(us[t], us[t + 1], us[t + 2], us[t + 3]);
;       }
	v_lshl_add_u32 v12, v17, 7, v12
	v_bfe_u32 v17, v152, 4, 4
	v_and_b32_e32 v11, 15, v152
	v_add_u32_e32 v17, v138, v17
	v_add_u32_e32 v11, v138, v11
	ds_read_u8 v17, v17
	ds_read_u8 v11, v11 offset:16
	s_waitcnt lgkmcnt(0)
	v_lshl_add_u32 v11, v17, 7, v11
	v_bfe_u32 v17, v151, 4, 4
	v_and_b32_e32 v10, 15, v151
	v_add_u32_e32 v17, v138, v17
	v_add_u32_e32 v10, v138, v10
	ds_read_u8 v17, v17
	ds_read_u8 v10, v10 offset:16
	s_waitcnt lgkmcnt(0)
	v_lshl_add_u32 v10, v17, 7, v10
	v_bfe_u32 v17, v150, 4, 4
	v_and_b32_e32 v16, 15, v150
	v_add_u32_e32 v17, v138, v17
	v_add_u32_e32 v16, v138, v16
	ds_read_u8 v17, v17
	ds_read_u8 v16, v16 offset:16
	s_waitcnt lgkmcnt(0)
	v_lshl_add_u32 v17, v17, 7, v16
	v_bfe_u32 v16, v149, 4, 4
	v_and_b32_e32 v15, 15, v149
	v_add_u32_e32 v16, v138, v16
	v_add_u32_e32 v15, v138, v15
	ds_read_u8 v16, v16
	ds_read_u8 v15, v15 offset:16
	s_waitcnt lgkmcnt(0)
	v_lshl_add_u32 v16, v16, 7, v15
	v_bfe_u32 v15, v164, 4, 4
	v_and_b32_e32 v14, 15, v164
	v_add_u32_e32 v15, v138, v15
	v_add_u32_e32 v14, v138, v14
	ds_read_u8 v15, v15
	ds_read_u8 v14, v14 offset:16
	s_waitcnt lgkmcnt(0)
	v_lshl_add_u32 v15, v15, 7, v14
	v_bfe_u32 v14, v148, 4, 4
	v_and_b32_e32 v0, 15, v148
	v_add_u32_e32 v14, v138, v14
	v_add_u32_e32 v0, v138, v0
	ds_read_u8 v14, v14
	ds_read_u8 v0, v0 offset:16
	s_waitcnt lgkmcnt(0)
	v_lshl_add_u32 v14, v14, 7, v0
	s_add_u32 s42, s6, 0x10000
	s_addc_u32 s43, s7, 0
	v_lshlrev_b32_e32 v0, 2, v14
	global_load_dword v18, v0, s[6:7]
	global_load_dword v122, v0, s[42:43]
	v_lshlrev_b32_e32 v0, 2, v15
	global_load_dword v19, v0, s[6:7]
	global_load_dword v123, v0, s[42:43]
	v_lshlrev_b32_e32 v0, 2, v16
	global_load_dword v20, v0, s[6:7]
	global_load_dword v126, v0, s[42:43]
	v_lshlrev_b32_e32 v0, 2, v17
	global_load_dword v21, v0, s[6:7]
	global_load_dword v127, v0, s[42:43]
	v_lshlrev_b32_e32 v0, 2, v10
	global_load_dword v22, v0, s[6:7]
	global_load_dword v124, v0, s[42:43]
	v_lshlrev_b32_e32 v0, 2, v11
	global_load_dword v23, v0, s[6:7]
	global_load_dword v125, v0, s[42:43]
	v_lshlrev_b32_e32 v0, 2, v12
	global_load_dword v24, v0, s[6:7]
	global_load_dword v128, v0, s[42:43]
	v_lshlrev_b32_e32 v0, 2, v13
	global_load_dword v25, v0, s[6:7]
	global_load_dword v129, v0, s[42:43]
	v_lshlrev_b32_e32 v0, 2, v6
	global_load_dword v26, v0, s[6:7]
	global_load_dword v130, v0, s[42:43]
	v_lshlrev_b32_e32 v0, 2, v7
	global_load_dword v27, v0, s[6:7]
	global_load_dword v131, v0, s[42:43]
	v_lshlrev_b32_e32 v0, 2, v8
	global_load_dword v28, v0, s[6:7]
	global_load_dword v132, v0, s[42:43]
	v_lshlrev_b32_e32 v0, 2, v9
	global_load_dword v29, v0, s[6:7]
	global_load_dword v133, v0, s[42:43]
	v_lshlrev_b32_e32 v0, 2, v2
	global_load_dword v30, v0, s[6:7]
	global_load_dword v134, v0, s[42:43]
	v_lshlrev_b32_e32 v0, 2, v3
	global_load_dword v31, v0, s[6:7]
	global_load_dword v135, v0, s[42:43]
	v_lshlrev_b32_e32 v0, 2, v4
	global_load_dword v32, v0, s[6:7]
	global_load_dword v136, v0, s[42:43]
	v_lshlrev_b32_e32 v0, 2, v5
	global_load_dword v33, v0, s[6:7]
	global_load_dword v137, v0, s[42:43]
	s_mov_b32 s17, 0x840000
	global_store_dwordx4 v[120:121], v[14:17], off
	s_nop 1
	v_pk_mul_f32 v[14:15], v[100:101], v[116:117] op_sel_hi:[1,0]
	v_pk_mul_f32 v[16:17], v[104:105], v[116:117] op_sel_hi:[1,0]
	s_waitcnt vmcnt(29)
	v_pk_mul_f32 v[14:15], v[14:15], v[122:123]
	s_waitcnt vmcnt(25)
	v_pk_mul_f32 v[16:17], v[16:17], v[126:127]
	global_store_dwordx4 v[118:119], v[14:17], off
	s_nop 1
	v_add_co_u32_e32 v14, vcc, s17, v118
	s_nop 1
	v_addc_co_u32_e32 v15, vcc, 0, v119, vcc
	global_store_dwordx4 v[14:15], v[18:21], off
	global_store_dwordx4 v[120:121], v[10:13], off offset:16
	s_nop 1
	v_pk_mul_f32 v[10:11], v[102:103], v[116:117] op_sel_hi:[1,0]
	v_pk_mul_f32 v[12:13], v[110:111], v[116:117] op_sel_hi:[1,0]
	s_waitcnt vmcnt(24)
	v_pk_mul_f32 v[10:11], v[10:11], v[124:125]
	s_waitcnt vmcnt(20)
	v_pk_mul_f32 v[12:13], v[12:13], v[128:129]
	global_store_dwordx4 v[118:119], v[10:13], off offset:16
	global_store_dwordx4 v[14:15], v[22:25], off offset:16
	global_store_dwordx4 v[120:121], v[6:9], off offset:32
	s_nop 1
	v_pk_mul_f32 v[6:7], v[112:113], v[116:117] op_sel_hi:[1,0]
	v_pk_mul_f32 v[8:9], v[114:115], v[116:117] op_sel_hi:[1,0]
	s_waitcnt vmcnt(19)
	v_pk_mul_f32 v[6:7], v[6:7], v[130:131]
	s_waitcnt vmcnt(15)
	v_pk_mul_f32 v[8:9], v[8:9], v[132:133]
	global_store_dwordx4 v[118:119], v[6:9], off offset:32
	global_store_dwordx4 v[14:15], v[26:29], off offset:32
	global_store_dwordx4 v[120:121], v[2:5], off offset:48
	s_nop 1
	v_pk_mul_f32 v[2:3], v[106:107], v[116:117] op_sel_hi:[1,0]
	v_pk_mul_f32 v[4:5], v[108:109], v[116:117] op_sel_hi:[1,0]
	s_waitcnt vmcnt(14)
	v_pk_mul_f32 v[2:3], v[2:3], v[134:135]
	s_waitcnt vmcnt(10)
	v_pk_mul_f32 v[4:5], v[4:5], v[136:137]
	global_store_dwordx4 v[118:119], v[2:5], off offset:48
	global_store_dwordx4 v[14:15], v[30:33], off offset:48
	s_branch .LBB0_627
